# stack of the individually validated bit-identical edits: shw_gemm DPP reduction + attention MFMA-cluster setprio + v_max3 softmax max chain + final_norm g-load hoist
# speedup vs baseline: 1.0033x; 1.0033x over previous
.LBB0_991:
	s_mul_i32 s40, s41, 0x2200
	v_add_u32_e32 v173, s40, v172
	ds_read_b128 v[66:69], v173
	ds_read_b128 v[174:177], v173 offset:32
	ds_read_b128 v[178:181], v173 offset:64
	ds_read_b128 v[182:185], v173 offset:96
	s_waitcnt lgkmcnt(3)
	s_setprio 1
	v_mfma_f32_32x32x16_bf16 v[66:81], v[66:69], v[82:85], 0
	s_waitcnt lgkmcnt(2)
	v_mfma_f32_32x32x16_bf16 v[66:81], v[174:177], v[86:89], v[66:81]
	s_waitcnt lgkmcnt(1)
	v_mfma_f32_32x32x16_bf16 v[66:81], v[178:181], v[90:93], v[66:81]
	s_waitcnt lgkmcnt(0)
	v_mfma_f32_32x32x16_bf16 v[66:81], v[182:185], v[94:97], v[66:81]
	ds_read_b128 v[174:177], v173 offset:128
	ds_read_b128 v[178:181], v173 offset:160
	ds_read_b128 v[182:185], v173 offset:192
	ds_read_b128 v[186:189], v173 offset:224
	s_waitcnt lgkmcnt(3)
	v_mfma_f32_32x32x16_bf16 v[66:81], v[174:177], v[98:101], v[66:81]
	s_waitcnt lgkmcnt(2)
	v_mfma_f32_32x32x16_bf16 v[66:81], v[178:181], v[102:105], v[66:81]
	s_waitcnt lgkmcnt(1)
	v_mfma_f32_32x32x16_bf16 v[66:81], v[182:185], v[106:109], v[66:81]
	s_waitcnt lgkmcnt(0)
	v_mfma_f32_32x32x16_bf16 v[66:81], v[186:189], v[110:113], v[66:81]
	s_setprio 0
	s_and_b64 vcc, exec, s[24:25]
	s_mov_b64 s[0:1], -1
	s_cbranch_vccz .LBB0_993
	s_nop 8
	v_max3_f32 v173, v66, v67, v68
	v_max3_f32 v174, v69, v70, v71
	v_max3_f32 v175, v72, v73, v74
	v_max3_f32 v176, v75, v76, v77
	v_max3_f32 v177, v78, v79, v80
	v_max3_f32 v173, v173, v174, v81
	v_max3_f32 v175, v175, v176, v177
	v_max_f32_e32 v173, v173, v175
	s_mov_b64 s[0:1], 0
